# FFN-up phase hand-written: 128x256 macro-tile (wave 64x128), LDS-DMA 3-stage ring k32, own SwiGLU epilogue; bf16 MFMA f32 acc unchanged
# speedup vs baseline: 1.0379x; 1.0312x over previous
.LBB0_2769:
	v_readlane_b32 s2, v246, 26
	s_cmp_eq_u32 s2, 10
	s_cselect_b64 s[8:9], -1, 0
	s_load_dwordx2 s[10:11], s[0:1], 0x108
	v_cndmask_b32_e64 v0, 0, 1, s[8:9]
	s_mov_b32 s2, s83
	v_readfirstlane_b32 s0, v0
	s_or_b32 s0, s58, s0
	s_mul_hi_i32 s1, s0, 0xb00000
	s_mul_i32 s0, s0, 0xb00000
	s_waitcnt lgkmcnt(0)
	s_add_u32 s0, s10, s0
	s_addc_u32 s1, s11, s1
	s_add_u32 s0, s0, 0x7c78100
	s_addc_u32 s1, s1, 0
	s_add_u32 s8, s10, 0x3000000
	s_addc_u32 s9, s11, 0
	s_add_u32 s10, s10, 0x14958100
	s_addc_u32 s11, s11, 0
	s_mov_b32 s14, 0x10000
	v_and_b32_e32 v171, 63, v194
	v_lshrrev_b32_e32 v172, 6, v194
	v_lshrrev_b32_e32 v160, 2, v194
	v_lshlrev_b32_e32 v160, 11, v160
	v_and_b32_e32 v173, 3, v171
	v_bfe_u32 v174, v171, 4, 2
	v_xor_b32_e32 v173, v173, v174
	v_lshl_add_u32 v160, v173, 4, v160
	v_add_u32_e32 v161, 0x20000, v160
	v_and_b32_e32 v175, 31, v171
	v_lshrrev_b32_e32 v176, 5, v171
	v_bfe_u32 v177, v175, 2, 2
	v_xor_b32_e32 v178, v176, v177
	v_xor_b32_e32 v179, 2, v178
	v_lshrrev_b32_e32 v180, 1, v172
	v_and_b32_e32 v181, 1, v172
	v_lshl_add_u32 v182, v180, 6, v175
	v_lshl_add_u32 v183, v181, 6, v175
	v_lshlrev_b32_e32 v182, 6, v182
	v_lshlrev_b32_e32 v183, 6, v183
	v_lshl_add_u32 v154, v178, 4, v182
	v_lshl_add_u32 v155, v179, 4, v182
	v_lshl_add_u32 v156, v178, 4, v183
	v_lshl_add_u32 v157, v179, 4, v183
	v_add_u32_e32 v158, 0x2000, v156
	v_add_u32_e32 v159, 0x2000, v157
	v_lshlrev_b32_e32 v184, 6, v180
	v_lshl_add_u32 v184, v176, 2, v184
	v_mul_u32_u24_e32 v184, 0x1600, v184
	v_lshl_add_u32 v185, v181, 5, v175
	v_lshl_add_u32 v162, v185, 1, v184
	v_add_u32_e32 v163, 0x1600, v162
	v_add_u32_e32 v164, 0x2c00, v162
	v_add_u32_e32 v165, 0x4200, v162
	v_readfirstlane_b32 s65, v194
	s_nop 0
	s_lshl_b32 s65, s65, 4
	s_add_u32 s65, s65, 16
	v_readlane_b32 s62, v246, 14
	s_mov_b32 s64, 0
.Lhw_ffnup_D:
	s_add_i32 s63, s64, s62
	s_cmpk_gt_u32 s63, 0x108
	s_cbranch_scc1 .Lhw_ffnup_Dd
	s_mov_b32 s64, s63
	s_branch .Lhw_ffnup_D
.Lhw_ffnup_Dd:
	s_mov_b32 s2, s83
.Lhw_ffnup_dloop:
	s_cmp_ge_u32 s2, s64
	s_cbranch_scc1 .Lhw_ffnup_tail
	s_mul_i32 s6, s2, 745
	s_lshr_b32 s6, s6, 16
	s_mul_i32 s14, s6, 88
	s_sub_i32 s14, s2, s14
	v_readlane_b32 s13, v246, 16
	s_lshl_b32 s6, s6, 2
	s_and_b32 s12, s14, 3
	s_add_i32 s6, s6, s12
	s_add_i32 s6, s6, s13
	s_lshl_b32 s6, s6, 7
	s_lshr_b32 s14, s14, 2
	s_lshl_b32 s14, s14, 8
	s_lshl_b32 vcc_lo, s6, 11
	s_add_u32 s66, s10, vcc_lo
	s_addc_u32 s67, s11, 0
	s_lshl_b32 vcc_lo, s14, 11
	s_add_u32 s12, s0, vcc_lo
	s_addc_u32 s13, s1, 0
	s_add_u32 s62, s12, 0x40000
	s_addc_u32 s63, s13, 0
	s_barrier
	s_add_u32 m0, s65, 0x0
	s_nop 0
	global_load_lds_dwordx4 v160, s[66:67]
	s_add_u32 m0, s65, 0x1000
	s_nop 0
	global_load_lds_dwordx4 v161, s[66:67]
	s_add_u32 m0, s65, 0x2000
	s_nop 0
	global_load_lds_dwordx4 v160, s[12:13]
	s_add_u32 m0, s65, 0x3000
	s_nop 0
	global_load_lds_dwordx4 v161, s[12:13]
	s_add_u32 m0, s65, 0x4000
	s_nop 0
	global_load_lds_dwordx4 v160, s[62:63]
	s_add_u32 m0, s65, 0x5000
	s_nop 0
	global_load_lds_dwordx4 v161, s[62:63]
	s_add_u32 s66, s66, 64
	s_addc_u32 s67, s67, 0
	s_add_u32 s12, s12, 64
	s_addc_u32 s13, s13, 0
	s_add_u32 s62, s62, 64
	s_addc_u32 s63, s63, 0
	s_add_u32 m0, s65, 0x6000
	s_nop 0
	global_load_lds_dwordx4 v160, s[66:67]
	s_add_u32 m0, s65, 0x7000
	s_nop 0
	global_load_lds_dwordx4 v161, s[66:67]
	s_add_u32 m0, s65, 0x8000
	s_nop 0
	global_load_lds_dwordx4 v160, s[12:13]
	s_add_u32 m0, s65, 0x9000
	s_nop 0
	global_load_lds_dwordx4 v161, s[12:13]
	s_add_u32 m0, s65, 0xa000
	s_nop 0
	global_load_lds_dwordx4 v160, s[62:63]
	s_add_u32 m0, s65, 0xb000
	s_nop 0
	global_load_lds_dwordx4 v161, s[62:63]
	s_add_u32 s66, s66, 64
	s_addc_u32 s67, s67, 0
	s_add_u32 s12, s12, 64
	s_addc_u32 s13, s13, 0
	s_add_u32 s62, s62, 64
	s_addc_u32 s63, s63, 0
	v_mov_b32_e32 v2, 0
	v_mov_b32_e32 v3, 0
	v_mov_b32_e32 v4, 0
	v_mov_b32_e32 v5, 0
	v_mov_b32_e32 v6, 0
	v_mov_b32_e32 v7, 0
	v_mov_b32_e32 v8, 0
	v_mov_b32_e32 v9, 0
	v_mov_b32_e32 v10, 0
	v_mov_b32_e32 v11, 0
	v_mov_b32_e32 v12, 0
	v_mov_b32_e32 v13, 0
	v_mov_b32_e32 v14, 0
	v_mov_b32_e32 v15, 0
	v_mov_b32_e32 v16, 0
	v_mov_b32_e32 v17, 0
	v_mov_b32_e32 v18, 0
	v_mov_b32_e32 v19, 0
	v_mov_b32_e32 v20, 0
	v_mov_b32_e32 v21, 0
	v_mov_b32_e32 v22, 0
	v_mov_b32_e32 v23, 0
	v_mov_b32_e32 v24, 0
	v_mov_b32_e32 v25, 0
	v_mov_b32_e32 v26, 0
	v_mov_b32_e32 v27, 0
	v_mov_b32_e32 v28, 0
	v_mov_b32_e32 v29, 0
	v_mov_b32_e32 v30, 0
	v_mov_b32_e32 v31, 0
	v_mov_b32_e32 v32, 0
	v_mov_b32_e32 v33, 0
	v_mov_b32_e32 v34, 0
	v_mov_b32_e32 v35, 0
	v_mov_b32_e32 v36, 0
	v_mov_b32_e32 v37, 0
	v_mov_b32_e32 v38, 0
	v_mov_b32_e32 v39, 0
	v_mov_b32_e32 v40, 0
	v_mov_b32_e32 v41, 0
	v_mov_b32_e32 v42, 0
	v_mov_b32_e32 v43, 0
	v_mov_b32_e32 v44, 0
	v_mov_b32_e32 v45, 0
	v_mov_b32_e32 v46, 0
	v_mov_b32_e32 v47, 0
	v_mov_b32_e32 v48, 0
	v_mov_b32_e32 v49, 0
	v_mov_b32_e32 v50, 0
	v_mov_b32_e32 v51, 0
	v_mov_b32_e32 v52, 0
	v_mov_b32_e32 v53, 0
	v_mov_b32_e32 v54, 0
	v_mov_b32_e32 v55, 0
	v_mov_b32_e32 v56, 0
	v_mov_b32_e32 v57, 0
	v_mov_b32_e32 v58, 0
	v_mov_b32_e32 v59, 0
	v_mov_b32_e32 v60, 0
	v_mov_b32_e32 v61, 0
	v_mov_b32_e32 v62, 0
	v_mov_b32_e32 v63, 0
	v_mov_b32_e32 v64, 0
	v_mov_b32_e32 v65, 0
	v_mov_b32_e32 v66, 0
	v_mov_b32_e32 v67, 0
	v_mov_b32_e32 v68, 0
	v_mov_b32_e32 v69, 0
	v_mov_b32_e32 v70, 0
	v_mov_b32_e32 v71, 0
	v_mov_b32_e32 v72, 0
	v_mov_b32_e32 v73, 0
	v_mov_b32_e32 v74, 0
	v_mov_b32_e32 v75, 0
	v_mov_b32_e32 v76, 0
	v_mov_b32_e32 v77, 0
	v_mov_b32_e32 v78, 0
	v_mov_b32_e32 v79, 0
	v_mov_b32_e32 v80, 0
	v_mov_b32_e32 v81, 0
	v_mov_b32_e32 v82, 0
	v_mov_b32_e32 v83, 0
	v_mov_b32_e32 v84, 0
	v_mov_b32_e32 v85, 0
	v_mov_b32_e32 v86, 0
	v_mov_b32_e32 v87, 0
	v_mov_b32_e32 v88, 0
	v_mov_b32_e32 v89, 0
	v_mov_b32_e32 v90, 0
	v_mov_b32_e32 v91, 0
	v_mov_b32_e32 v92, 0
	v_mov_b32_e32 v93, 0
	v_mov_b32_e32 v94, 0
	v_mov_b32_e32 v95, 0
	v_mov_b32_e32 v96, 0
	v_mov_b32_e32 v97, 0
	v_mov_b32_e32 v98, 0
	v_mov_b32_e32 v99, 0
	v_mov_b32_e32 v100, 0
	v_mov_b32_e32 v101, 0
	v_mov_b32_e32 v102, 0
	v_mov_b32_e32 v103, 0
	v_mov_b32_e32 v104, 0
	v_mov_b32_e32 v105, 0
	v_mov_b32_e32 v106, 0
	v_mov_b32_e32 v107, 0
	v_mov_b32_e32 v108, 0
	v_mov_b32_e32 v109, 0
	v_mov_b32_e32 v110, 0
	v_mov_b32_e32 v111, 0
	v_mov_b32_e32 v112, 0
	v_mov_b32_e32 v113, 0
	v_mov_b32_e32 v114, 0
	v_mov_b32_e32 v115, 0
	v_mov_b32_e32 v116, 0
	v_mov_b32_e32 v117, 0
	v_mov_b32_e32 v118, 0
	v_mov_b32_e32 v119, 0
	v_mov_b32_e32 v120, 0
	v_mov_b32_e32 v121, 0
	v_mov_b32_e32 v122, 0
	v_mov_b32_e32 v123, 0
	v_mov_b32_e32 v124, 0
	v_mov_b32_e32 v125, 0
	v_mov_b32_e32 v126, 0
	v_mov_b32_e32 v127, 0
	v_mov_b32_e32 v128, 0
	v_mov_b32_e32 v129, 0
	s_waitcnt vmcnt(6)
	s_barrier
	ds_read_b128 v[130:133], v154 offset:16
	ds_read_b128 v[138:141], v156 offset:8208
	ds_read_b128 v[142:145], v156 offset:10256
	ds_read_b128 v[134:137], v154 offset:2064
	ds_read_b128 v[146:149], v158 offset:8208
	ds_read_b128 v[150:153], v158 offset:10256
	s_mov_b32 s59, 10
.Lhw_ffnup_d_loop:
	s_waitcnt vmcnt(0)
	s_barrier
	s_waitcnt lgkmcnt(0)
	v_mfma_f32_32x32x16_bf16 v[2:17], v[130:133], v[138:141], v[2:17]
	ds_read_b128 v[212:215], v155 offset:16
	s_add_u32 m0, s65, 0xc000
	v_mfma_f32_32x32x16_bf16 v[18:33], v[130:133], v[142:145], v[18:33]
	ds_read_b128 v[220:223], v157 offset:8208
	global_load_lds_dwordx4 v160, s[66:67]
	v_mfma_f32_32x32x16_bf16 v[34:49], v[134:137], v[138:141], v[34:49]
	ds_read_b128 v[224:227], v157 offset:10256
	s_add_u32 m0, s65, 0xd000
	v_mfma_f32_32x32x16_bf16 v[50:65], v[134:137], v[142:145], v[50:65]
	ds_read_b128 v[216:219], v155 offset:2064
	global_load_lds_dwordx4 v161, s[66:67]
	v_mfma_f32_32x32x16_bf16 v[66:81], v[130:133], v[146:149], v[66:81]
	ds_read_b128 v[228:231], v159 offset:8208
	s_add_u32 m0, s65, 0xe000
	v_mfma_f32_32x32x16_bf16 v[82:97], v[130:133], v[150:153], v[82:97]
	ds_read_b128 v[232:235], v159 offset:10256
	global_load_lds_dwordx4 v160, s[12:13]
	v_mfma_f32_32x32x16_bf16 v[98:113], v[134:137], v[146:149], v[98:113]
	s_add_u32 m0, s65, 0xf000
	v_mfma_f32_32x32x16_bf16 v[114:129], v[134:137], v[150:153], v[114:129]
	global_load_lds_dwordx4 v161, s[12:13]
	s_waitcnt lgkmcnt(4)
	v_mfma_f32_32x32x16_bf16 v[2:17], v[212:215], v[220:223], v[2:17]
	s_add_u32 m0, s65, 0x10000
	ds_read_b128 v[130:133], v154 offset:24592
	s_waitcnt lgkmcnt(4)
	v_mfma_f32_32x32x16_bf16 v[18:33], v[212:215], v[224:227], v[18:33]
	global_load_lds_dwordx4 v160, s[62:63]
	ds_read_b128 v[138:141], v156 offset:32784
	s_waitcnt lgkmcnt(4)
	v_mfma_f32_32x32x16_bf16 v[34:49], v[216:219], v[220:223], v[34:49]
	s_add_u32 m0, s65, 0x11000
	ds_read_b128 v[142:145], v156 offset:34832
	s_waitcnt lgkmcnt(5)
	v_mfma_f32_32x32x16_bf16 v[50:65], v[216:219], v[224:227], v[50:65]
	global_load_lds_dwordx4 v161, s[62:63]
	ds_read_b128 v[134:137], v154 offset:26640
	s_waitcnt lgkmcnt(5)
	v_mfma_f32_32x32x16_bf16 v[66:81], v[212:215], v[228:231], v[66:81]
	s_add_u32 s66, s66, 64
	s_addc_u32 s67, s67, 0
	ds_read_b128 v[146:149], v158 offset:32784
	s_waitcnt lgkmcnt(5)
	v_mfma_f32_32x32x16_bf16 v[82:97], v[212:215], v[232:235], v[82:97]
	s_add_u32 s12, s12, 64
	s_addc_u32 s13, s13, 0
	ds_read_b128 v[150:153], v158 offset:34832
	s_waitcnt lgkmcnt(7)
	v_mfma_f32_32x32x16_bf16 v[98:113], v[216:219], v[228:231], v[98:113]
	s_add_u32 s62, s62, 64
	s_addc_u32 s63, s63, 0
	s_waitcnt lgkmcnt(6)
	v_mfma_f32_32x32x16_bf16 v[114:129], v[216:219], v[232:235], v[114:129]
	s_waitcnt vmcnt(0)
	s_barrier
	s_waitcnt lgkmcnt(0)
	v_mfma_f32_32x32x16_bf16 v[2:17], v[130:133], v[138:141], v[2:17]
	ds_read_b128 v[212:215], v155 offset:24592
	s_add_u32 m0, s65, 0x0
	v_mfma_f32_32x32x16_bf16 v[18:33], v[130:133], v[142:145], v[18:33]
	ds_read_b128 v[220:223], v157 offset:32784
	global_load_lds_dwordx4 v160, s[66:67]
	v_mfma_f32_32x32x16_bf16 v[34:49], v[134:137], v[138:141], v[34:49]
	ds_read_b128 v[224:227], v157 offset:34832
	s_add_u32 m0, s65, 0x1000
	v_mfma_f32_32x32x16_bf16 v[50:65], v[134:137], v[142:145], v[50:65]
	ds_read_b128 v[216:219], v155 offset:26640
	global_load_lds_dwordx4 v161, s[66:67]
	v_mfma_f32_32x32x16_bf16 v[66:81], v[130:133], v[146:149], v[66:81]
	ds_read_b128 v[228:231], v159 offset:32784
	s_add_u32 m0, s65, 0x2000
	v_mfma_f32_32x32x16_bf16 v[82:97], v[130:133], v[150:153], v[82:97]
	ds_read_b128 v[232:235], v159 offset:34832
	global_load_lds_dwordx4 v160, s[12:13]
	v_mfma_f32_32x32x16_bf16 v[98:113], v[134:137], v[146:149], v[98:113]
	s_add_u32 m0, s65, 0x3000
	v_mfma_f32_32x32x16_bf16 v[114:129], v[134:137], v[150:153], v[114:129]
	global_load_lds_dwordx4 v161, s[12:13]
	s_waitcnt lgkmcnt(4)
	v_mfma_f32_32x32x16_bf16 v[2:17], v[212:215], v[220:223], v[2:17]
	s_add_u32 m0, s65, 0x4000
	ds_read_b128 v[130:133], v154 offset:49168
	s_waitcnt lgkmcnt(4)
	v_mfma_f32_32x32x16_bf16 v[18:33], v[212:215], v[224:227], v[18:33]
	global_load_lds_dwordx4 v160, s[62:63]
	ds_read_b128 v[138:141], v156 offset:57360
	s_waitcnt lgkmcnt(4)
	v_mfma_f32_32x32x16_bf16 v[34:49], v[216:219], v[220:223], v[34:49]
	s_add_u32 m0, s65, 0x5000
	ds_read_b128 v[142:145], v156 offset:59408
	s_waitcnt lgkmcnt(5)
	v_mfma_f32_32x32x16_bf16 v[50:65], v[216:219], v[224:227], v[50:65]
	global_load_lds_dwordx4 v161, s[62:63]
	ds_read_b128 v[134:137], v154 offset:51216
	s_waitcnt lgkmcnt(5)
	v_mfma_f32_32x32x16_bf16 v[66:81], v[212:215], v[228:231], v[66:81]
	s_add_u32 s66, s66, 64
	s_addc_u32 s67, s67, 0
	ds_read_b128 v[146:149], v158 offset:57360
	s_waitcnt lgkmcnt(5)
	v_mfma_f32_32x32x16_bf16 v[82:97], v[212:215], v[232:235], v[82:97]
	s_add_u32 s12, s12, 64
	s_addc_u32 s13, s13, 0
	ds_read_b128 v[150:153], v158 offset:59408
	s_waitcnt lgkmcnt(7)
	v_mfma_f32_32x32x16_bf16 v[98:113], v[216:219], v[228:231], v[98:113]
	s_add_u32 s62, s62, 64
	s_addc_u32 s63, s63, 0
	s_waitcnt lgkmcnt(6)
	v_mfma_f32_32x32x16_bf16 v[114:129], v[216:219], v[232:235], v[114:129]
	s_waitcnt vmcnt(0)
	s_barrier
	s_waitcnt lgkmcnt(0)
	v_mfma_f32_32x32x16_bf16 v[2:17], v[130:133], v[138:141], v[2:17]
	ds_read_b128 v[212:215], v155 offset:49168
	s_add_u32 m0, s65, 0x6000
	v_mfma_f32_32x32x16_bf16 v[18:33], v[130:133], v[142:145], v[18:33]
	ds_read_b128 v[220:223], v157 offset:57360
	global_load_lds_dwordx4 v160, s[66:67]
	v_mfma_f32_32x32x16_bf16 v[34:49], v[134:137], v[138:141], v[34:49]
	ds_read_b128 v[224:227], v157 offset:59408
	s_add_u32 m0, s65, 0x7000
	v_mfma_f32_32x32x16_bf16 v[50:65], v[134:137], v[142:145], v[50:65]
	ds_read_b128 v[216:219], v155 offset:51216
	global_load_lds_dwordx4 v161, s[66:67]
	v_mfma_f32_32x32x16_bf16 v[66:81], v[130:133], v[146:149], v[66:81]
	ds_read_b128 v[228:231], v159 offset:57360
	s_add_u32 m0, s65, 0x8000
	v_mfma_f32_32x32x16_bf16 v[82:97], v[130:133], v[150:153], v[82:97]
	ds_read_b128 v[232:235], v159 offset:59408
	global_load_lds_dwordx4 v160, s[12:13]
	v_mfma_f32_32x32x16_bf16 v[98:113], v[134:137], v[146:149], v[98:113]
	s_add_u32 m0, s65, 0x9000
	v_mfma_f32_32x32x16_bf16 v[114:129], v[134:137], v[150:153], v[114:129]
	global_load_lds_dwordx4 v161, s[12:13]
	s_waitcnt lgkmcnt(4)
	v_mfma_f32_32x32x16_bf16 v[2:17], v[212:215], v[220:223], v[2:17]
	s_add_u32 m0, s65, 0xa000
	ds_read_b128 v[130:133], v154 offset:16
	s_waitcnt lgkmcnt(4)
	v_mfma_f32_32x32x16_bf16 v[18:33], v[212:215], v[224:227], v[18:33]
	global_load_lds_dwordx4 v160, s[62:63]
	ds_read_b128 v[138:141], v156 offset:8208
	s_waitcnt lgkmcnt(4)
	v_mfma_f32_32x32x16_bf16 v[34:49], v[216:219], v[220:223], v[34:49]
	s_add_u32 m0, s65, 0xb000
	ds_read_b128 v[142:145], v156 offset:10256
	s_waitcnt lgkmcnt(5)
	v_mfma_f32_32x32x16_bf16 v[50:65], v[216:219], v[224:227], v[50:65]
	global_load_lds_dwordx4 v161, s[62:63]
	ds_read_b128 v[134:137], v154 offset:2064
	s_waitcnt lgkmcnt(5)
	v_mfma_f32_32x32x16_bf16 v[66:81], v[212:215], v[228:231], v[66:81]
	s_add_u32 s66, s66, 64
	s_addc_u32 s67, s67, 0
	ds_read_b128 v[146:149], v158 offset:8208
	s_waitcnt lgkmcnt(5)
	v_mfma_f32_32x32x16_bf16 v[82:97], v[212:215], v[232:235], v[82:97]
	s_add_u32 s12, s12, 64
	s_addc_u32 s13, s13, 0
	ds_read_b128 v[150:153], v158 offset:10256
	s_waitcnt lgkmcnt(7)
	v_mfma_f32_32x32x16_bf16 v[98:113], v[216:219], v[228:231], v[98:113]
	s_add_u32 s62, s62, 64
	s_addc_u32 s63, s63, 0
	s_waitcnt lgkmcnt(6)
	v_mfma_f32_32x32x16_bf16 v[114:129], v[216:219], v[232:235], v[114:129]
	s_sub_u32 s59, s59, 1
	s_cmp_lg_u32 s59, 0
	s_cbranch_scc1 .Lhw_ffnup_d_loop
	s_waitcnt vmcnt(0)
	s_barrier
	s_waitcnt lgkmcnt(0)
	v_mfma_f32_32x32x16_bf16 v[2:17], v[130:133], v[138:141], v[2:17]
	ds_read_b128 v[212:215], v155 offset:16
	v_mfma_f32_32x32x16_bf16 v[18:33], v[130:133], v[142:145], v[18:33]
	ds_read_b128 v[220:223], v157 offset:8208
	v_mfma_f32_32x32x16_bf16 v[34:49], v[134:137], v[138:141], v[34:49]
	ds_read_b128 v[224:227], v157 offset:10256
	v_mfma_f32_32x32x16_bf16 v[50:65], v[134:137], v[142:145], v[50:65]
	ds_read_b128 v[216:219], v155 offset:2064
	v_mfma_f32_32x32x16_bf16 v[66:81], v[130:133], v[146:149], v[66:81]
	ds_read_b128 v[228:231], v159 offset:8208
	v_mfma_f32_32x32x16_bf16 v[82:97], v[130:133], v[150:153], v[82:97]
	ds_read_b128 v[232:235], v159 offset:10256
	v_mfma_f32_32x32x16_bf16 v[98:113], v[134:137], v[146:149], v[98:113]
	v_mfma_f32_32x32x16_bf16 v[114:129], v[134:137], v[150:153], v[114:129]
	s_waitcnt lgkmcnt(4)
	v_mfma_f32_32x32x16_bf16 v[2:17], v[212:215], v[220:223], v[2:17]
	ds_read_b128 v[130:133], v154 offset:24592
	s_waitcnt lgkmcnt(4)
	v_mfma_f32_32x32x16_bf16 v[18:33], v[212:215], v[224:227], v[18:33]
	ds_read_b128 v[138:141], v156 offset:32784
	s_waitcnt lgkmcnt(4)
	v_mfma_f32_32x32x16_bf16 v[34:49], v[216:219], v[220:223], v[34:49]
	ds_read_b128 v[142:145], v156 offset:34832
	s_waitcnt lgkmcnt(5)
	v_mfma_f32_32x32x16_bf16 v[50:65], v[216:219], v[224:227], v[50:65]
	ds_read_b128 v[134:137], v154 offset:26640
	s_waitcnt lgkmcnt(5)
	v_mfma_f32_32x32x16_bf16 v[66:81], v[212:215], v[228:231], v[66:81]
	ds_read_b128 v[146:149], v158 offset:32784
	s_waitcnt lgkmcnt(5)
	v_mfma_f32_32x32x16_bf16 v[82:97], v[212:215], v[232:235], v[82:97]
	ds_read_b128 v[150:153], v158 offset:34832
	s_waitcnt lgkmcnt(7)
	v_mfma_f32_32x32x16_bf16 v[98:113], v[216:219], v[228:231], v[98:113]
	s_waitcnt lgkmcnt(6)
	v_mfma_f32_32x32x16_bf16 v[114:129], v[216:219], v[232:235], v[114:129]
	s_waitcnt lgkmcnt(0)
	v_mfma_f32_32x32x16_bf16 v[2:17], v[130:133], v[138:141], v[2:17]
	ds_read_b128 v[212:215], v155 offset:24592
	v_mfma_f32_32x32x16_bf16 v[18:33], v[130:133], v[142:145], v[18:33]
	ds_read_b128 v[220:223], v157 offset:32784
	v_mfma_f32_32x32x16_bf16 v[34:49], v[134:137], v[138:141], v[34:49]
	ds_read_b128 v[224:227], v157 offset:34832
	v_mfma_f32_32x32x16_bf16 v[50:65], v[134:137], v[142:145], v[50:65]
	ds_read_b128 v[216:219], v155 offset:26640
	v_mfma_f32_32x32x16_bf16 v[66:81], v[130:133], v[146:149], v[66:81]
	ds_read_b128 v[228:231], v159 offset:32784
	v_mfma_f32_32x32x16_bf16 v[82:97], v[130:133], v[150:153], v[82:97]
	ds_read_b128 v[232:235], v159 offset:34832
	v_mfma_f32_32x32x16_bf16 v[98:113], v[134:137], v[146:149], v[98:113]
	v_mfma_f32_32x32x16_bf16 v[114:129], v[134:137], v[150:153], v[114:129]
	s_waitcnt lgkmcnt(4)
	v_mfma_f32_32x32x16_bf16 v[2:17], v[212:215], v[220:223], v[2:17]
	s_waitcnt lgkmcnt(3)
	v_mfma_f32_32x32x16_bf16 v[18:33], v[212:215], v[224:227], v[18:33]
	s_waitcnt lgkmcnt(2)
	v_mfma_f32_32x32x16_bf16 v[34:49], v[216:219], v[220:223], v[34:49]
	s_waitcnt lgkmcnt(2)
	v_mfma_f32_32x32x16_bf16 v[50:65], v[216:219], v[224:227], v[50:65]
	s_waitcnt lgkmcnt(1)
	v_mfma_f32_32x32x16_bf16 v[66:81], v[212:215], v[228:231], v[66:81]
	s_waitcnt lgkmcnt(0)
	v_mfma_f32_32x32x16_bf16 v[82:97], v[212:215], v[232:235], v[82:97]
	s_waitcnt lgkmcnt(1)
	v_mfma_f32_32x32x16_bf16 v[98:113], v[216:219], v[228:231], v[98:113]
	s_waitcnt lgkmcnt(0)
	v_mfma_f32_32x32x16_bf16 v[114:129], v[216:219], v[232:235], v[114:129]
	s_nop 7
	s_nop 7
	s_mul_i32 vcc_lo, s6, 0x1600
	s_add_u32 s66, s8, vcc_lo
	s_addc_u32 s67, s9, 0
	s_add_u32 s66, s66, s14
	s_addc_u32 s67, s67, 0
	v_mul_f32_e32 v171, 0xbfb8aa3b, v2
	v_mul_f32_e32 v172, 0xbfb8aa3b, v3
	v_mul_f32_e32 v173, 0xbfb8aa3b, v4
	v_mul_f32_e32 v174, 0xbfb8aa3b, v5
	v_exp_f32_e32 v171, v171
	v_exp_f32_e32 v172, v172
	v_exp_f32_e32 v173, v173
	v_exp_f32_e32 v174, v174
	s_nop 0
	v_add_f32_e32 v171, 1.0, v171
	v_add_f32_e32 v172, 1.0, v172
	v_add_f32_e32 v173, 1.0, v173
	v_add_f32_e32 v174, 1.0, v174
	v_rcp_f32_e32 v171, v171
	v_rcp_f32_e32 v172, v172
	v_rcp_f32_e32 v173, v173
	v_rcp_f32_e32 v174, v174
	s_nop 0
	v_mul_f32_e32 v171, v2, v171
	v_mul_f32_e32 v172, v3, v172
	v_mul_f32_e32 v173, v4, v173
	v_mul_f32_e32 v174, v5, v174
	v_mul_f32_e32 v171, v18, v171
	v_mul_f32_e32 v172, v19, v172
	v_mul_f32_e32 v173, v20, v173
	v_mul_f32_e32 v174, v21, v174
	v_cvt_pk_bf16_f32 v179, v171, v171
	v_cvt_pk_bf16_f32 v180, v172, v172
	v_cvt_pk_bf16_f32 v181, v173, v173
	v_cvt_pk_bf16_f32 v182, v174, v174
	global_store_short v162, v179, s[66:67]
	global_store_short v163, v180, s[66:67]
	global_store_short v164, v181, s[66:67]
	global_store_short v165, v182, s[66:67]
	s_add_u32 s66, s66, 0xb000
	s_addc_u32 s67, s67, 0
	v_mul_f32_e32 v171, 0xbfb8aa3b, v6
	v_mul_f32_e32 v172, 0xbfb8aa3b, v7
	v_mul_f32_e32 v173, 0xbfb8aa3b, v8
	v_mul_f32_e32 v174, 0xbfb8aa3b, v9
	v_exp_f32_e32 v171, v171
	v_exp_f32_e32 v172, v172
	v_exp_f32_e32 v173, v173
	v_exp_f32_e32 v174, v174
	s_nop 0
	v_add_f32_e32 v171, 1.0, v171
	v_add_f32_e32 v172, 1.0, v172
	v_add_f32_e32 v173, 1.0, v173
	v_add_f32_e32 v174, 1.0, v174
	v_rcp_f32_e32 v171, v171
	v_rcp_f32_e32 v172, v172
	v_rcp_f32_e32 v173, v173
	v_rcp_f32_e32 v174, v174
	s_nop 0
	v_mul_f32_e32 v171, v6, v171
	v_mul_f32_e32 v172, v7, v172
	v_mul_f32_e32 v173, v8, v173
	v_mul_f32_e32 v174, v9, v174
	v_mul_f32_e32 v171, v22, v171
	v_mul_f32_e32 v172, v23, v172
	v_mul_f32_e32 v173, v24, v173
	v_mul_f32_e32 v174, v25, v174
	v_cvt_pk_bf16_f32 v179, v171, v171
	v_cvt_pk_bf16_f32 v180, v172, v172
	v_cvt_pk_bf16_f32 v181, v173, v173
	v_cvt_pk_bf16_f32 v182, v174, v174
	global_store_short v162, v179, s[66:67]
	global_store_short v163, v180, s[66:67]
	global_store_short v164, v181, s[66:67]
	global_store_short v165, v182, s[66:67]
	s_add_u32 s66, s66, 0xb000
	s_addc_u32 s67, s67, 0
	v_mul_f32_e32 v171, 0xbfb8aa3b, v10
	v_mul_f32_e32 v172, 0xbfb8aa3b, v11
	v_mul_f32_e32 v173, 0xbfb8aa3b, v12
	v_mul_f32_e32 v174, 0xbfb8aa3b, v13
	v_exp_f32_e32 v171, v171
	v_exp_f32_e32 v172, v172
	v_exp_f32_e32 v173, v173
	v_exp_f32_e32 v174, v174
	s_nop 0
	v_add_f32_e32 v171, 1.0, v171
	v_add_f32_e32 v172, 1.0, v172
	v_add_f32_e32 v173, 1.0, v173
	v_add_f32_e32 v174, 1.0, v174
	v_rcp_f32_e32 v171, v171
	v_rcp_f32_e32 v172, v172
	v_rcp_f32_e32 v173, v173
	v_rcp_f32_e32 v174, v174
	s_nop 0
	v_mul_f32_e32 v171, v10, v171
	v_mul_f32_e32 v172, v11, v172
	v_mul_f32_e32 v173, v12, v173
	v_mul_f32_e32 v174, v13, v174
	v_mul_f32_e32 v171, v26, v171
	v_mul_f32_e32 v172, v27, v172
	v_mul_f32_e32 v173, v28, v173
	v_mul_f32_e32 v174, v29, v174
	v_cvt_pk_bf16_f32 v179, v171, v171
	v_cvt_pk_bf16_f32 v180, v172, v172
	v_cvt_pk_bf16_f32 v181, v173, v173
	v_cvt_pk_bf16_f32 v182, v174, v174
	global_store_short v162, v179, s[66:67]
	global_store_short v163, v180, s[66:67]
	global_store_short v164, v181, s[66:67]
	global_store_short v165, v182, s[66:67]
	s_add_u32 s66, s66, 0xb000
	s_addc_u32 s67, s67, 0
	v_mul_f32_e32 v171, 0xbfb8aa3b, v14
	v_mul_f32_e32 v172, 0xbfb8aa3b, v15
	v_mul_f32_e32 v173, 0xbfb8aa3b, v16
	v_mul_f32_e32 v174, 0xbfb8aa3b, v17
	v_exp_f32_e32 v171, v171
	v_exp_f32_e32 v172, v172
	v_exp_f32_e32 v173, v173
	v_exp_f32_e32 v174, v174
	s_nop 0
	v_add_f32_e32 v171, 1.0, v171
	v_add_f32_e32 v172, 1.0, v172
	v_add_f32_e32 v173, 1.0, v173
	v_add_f32_e32 v174, 1.0, v174
	v_rcp_f32_e32 v171, v171
	v_rcp_f32_e32 v172, v172
	v_rcp_f32_e32 v173, v173
	v_rcp_f32_e32 v174, v174
	s_nop 0
	v_mul_f32_e32 v171, v14, v171
	v_mul_f32_e32 v172, v15, v172
	v_mul_f32_e32 v173, v16, v173
	v_mul_f32_e32 v174, v17, v174
	v_mul_f32_e32 v171, v30, v171
	v_mul_f32_e32 v172, v31, v172
	v_mul_f32_e32 v173, v32, v173
	v_mul_f32_e32 v174, v33, v174
	v_cvt_pk_bf16_f32 v179, v171, v171
	v_cvt_pk_bf16_f32 v180, v172, v172
	v_cvt_pk_bf16_f32 v181, v173, v173
	v_cvt_pk_bf16_f32 v182, v174, v174
	global_store_short v162, v179, s[66:67]
	global_store_short v163, v180, s[66:67]
	global_store_short v164, v181, s[66:67]
	global_store_short v165, v182, s[66:67]
	s_add_u32 s66, s66, 0xb000
	s_addc_u32 s67, s67, 0
	v_mul_f32_e32 v171, 0xbfb8aa3b, v34
	v_mul_f32_e32 v172, 0xbfb8aa3b, v35
	v_mul_f32_e32 v173, 0xbfb8aa3b, v36
	v_mul_f32_e32 v174, 0xbfb8aa3b, v37
	v_exp_f32_e32 v171, v171
	v_exp_f32_e32 v172, v172
	v_exp_f32_e32 v173, v173
	v_exp_f32_e32 v174, v174
	s_nop 0
	v_add_f32_e32 v171, 1.0, v171
	v_add_f32_e32 v172, 1.0, v172
	v_add_f32_e32 v173, 1.0, v173
	v_add_f32_e32 v174, 1.0, v174
	v_rcp_f32_e32 v171, v171
	v_rcp_f32_e32 v172, v172
	v_rcp_f32_e32 v173, v173
	v_rcp_f32_e32 v174, v174
	s_nop 0
	v_mul_f32_e32 v171, v34, v171
	v_mul_f32_e32 v172, v35, v172
	v_mul_f32_e32 v173, v36, v173
	v_mul_f32_e32 v174, v37, v174
	v_mul_f32_e32 v171, v50, v171
	v_mul_f32_e32 v172, v51, v172
	v_mul_f32_e32 v173, v52, v173
	v_mul_f32_e32 v174, v53, v174
	v_cvt_pk_bf16_f32 v179, v171, v171
	v_cvt_pk_bf16_f32 v180, v172, v172
	v_cvt_pk_bf16_f32 v181, v173, v173
	v_cvt_pk_bf16_f32 v182, v174, v174
	global_store_short v162, v179, s[66:67]
	global_store_short v163, v180, s[66:67]
	global_store_short v164, v181, s[66:67]
	global_store_short v165, v182, s[66:67]
	s_add_u32 s66, s66, 0xb000
	s_addc_u32 s67, s67, 0
	v_mul_f32_e32 v171, 0xbfb8aa3b, v38
	v_mul_f32_e32 v172, 0xbfb8aa3b, v39
	v_mul_f32_e32 v173, 0xbfb8aa3b, v40
	v_mul_f32_e32 v174, 0xbfb8aa3b, v41
	v_exp_f32_e32 v171, v171
	v_exp_f32_e32 v172, v172
	v_exp_f32_e32 v173, v173
	v_exp_f32_e32 v174, v174
	s_nop 0
	v_add_f32_e32 v171, 1.0, v171
	v_add_f32_e32 v172, 1.0, v172
	v_add_f32_e32 v173, 1.0, v173
	v_add_f32_e32 v174, 1.0, v174
	v_rcp_f32_e32 v171, v171
	v_rcp_f32_e32 v172, v172
	v_rcp_f32_e32 v173, v173
	v_rcp_f32_e32 v174, v174
	s_nop 0
	v_mul_f32_e32 v171, v38, v171
	v_mul_f32_e32 v172, v39, v172
	v_mul_f32_e32 v173, v40, v173
	v_mul_f32_e32 v174, v41, v174
	v_mul_f32_e32 v171, v54, v171
	v_mul_f32_e32 v172, v55, v172
	v_mul_f32_e32 v173, v56, v173
	v_mul_f32_e32 v174, v57, v174
	v_cvt_pk_bf16_f32 v179, v171, v171
	v_cvt_pk_bf16_f32 v180, v172, v172
	v_cvt_pk_bf16_f32 v181, v173, v173
	v_cvt_pk_bf16_f32 v182, v174, v174
	global_store_short v162, v179, s[66:67]
	global_store_short v163, v180, s[66:67]
	global_store_short v164, v181, s[66:67]
	global_store_short v165, v182, s[66:67]
	s_add_u32 s66, s66, 0xb000
	s_addc_u32 s67, s67, 0
	v_mul_f32_e32 v171, 0xbfb8aa3b, v42
	v_mul_f32_e32 v172, 0xbfb8aa3b, v43
	v_mul_f32_e32 v173, 0xbfb8aa3b, v44
	v_mul_f32_e32 v174, 0xbfb8aa3b, v45
	v_exp_f32_e32 v171, v171
	v_exp_f32_e32 v172, v172
	v_exp_f32_e32 v173, v173
	v_exp_f32_e32 v174, v174
	s_nop 0
	v_add_f32_e32 v171, 1.0, v171
	v_add_f32_e32 v172, 1.0, v172
	v_add_f32_e32 v173, 1.0, v173
	v_add_f32_e32 v174, 1.0, v174
	v_rcp_f32_e32 v171, v171
	v_rcp_f32_e32 v172, v172
	v_rcp_f32_e32 v173, v173
	v_rcp_f32_e32 v174, v174
	s_nop 0
	v_mul_f32_e32 v171, v42, v171
	v_mul_f32_e32 v172, v43, v172
	v_mul_f32_e32 v173, v44, v173
	v_mul_f32_e32 v174, v45, v174
	v_mul_f32_e32 v171, v58, v171
	v_mul_f32_e32 v172, v59, v172
	v_mul_f32_e32 v173, v60, v173
	v_mul_f32_e32 v174, v61, v174
	v_cvt_pk_bf16_f32 v179, v171, v171
	v_cvt_pk_bf16_f32 v180, v172, v172
	v_cvt_pk_bf16_f32 v181, v173, v173
	v_cvt_pk_bf16_f32 v182, v174, v174
	global_store_short v162, v179, s[66:67]
	global_store_short v163, v180, s[66:67]
	global_store_short v164, v181, s[66:67]
	global_store_short v165, v182, s[66:67]
	s_add_u32 s66, s66, 0xb000
	s_addc_u32 s67, s67, 0
	v_mul_f32_e32 v171, 0xbfb8aa3b, v46
	v_mul_f32_e32 v172, 0xbfb8aa3b, v47
	v_mul_f32_e32 v173, 0xbfb8aa3b, v48
	v_mul_f32_e32 v174, 0xbfb8aa3b, v49
	v_exp_f32_e32 v171, v171
	v_exp_f32_e32 v172, v172
	v_exp_f32_e32 v173, v173
	v_exp_f32_e32 v174, v174
	s_nop 0
	v_add_f32_e32 v171, 1.0, v171
	v_add_f32_e32 v172, 1.0, v172
	v_add_f32_e32 v173, 1.0, v173
	v_add_f32_e32 v174, 1.0, v174
	v_rcp_f32_e32 v171, v171
	v_rcp_f32_e32 v172, v172
	v_rcp_f32_e32 v173, v173
	v_rcp_f32_e32 v174, v174
	s_nop 0
	v_mul_f32_e32 v171, v46, v171
	v_mul_f32_e32 v172, v47, v172
	v_mul_f32_e32 v173, v48, v173
	v_mul_f32_e32 v174, v49, v174
	v_mul_f32_e32 v171, v62, v171
	v_mul_f32_e32 v172, v63, v172
	v_mul_f32_e32 v173, v64, v173
	v_mul_f32_e32 v174, v65, v174
	v_cvt_pk_bf16_f32 v179, v171, v171
	v_cvt_pk_bf16_f32 v180, v172, v172
	v_cvt_pk_bf16_f32 v181, v173, v173
	v_cvt_pk_bf16_f32 v182, v174, v174
	global_store_short v162, v179, s[66:67]
	global_store_short v163, v180, s[66:67]
	global_store_short v164, v181, s[66:67]
	global_store_short v165, v182, s[66:67]
	s_sub_u32 s66, s66, 0x4cf80
	s_subb_u32 s67, s67, 0
	v_mul_f32_e32 v171, 0xbfb8aa3b, v66
	v_mul_f32_e32 v172, 0xbfb8aa3b, v67
	v_mul_f32_e32 v173, 0xbfb8aa3b, v68
	v_mul_f32_e32 v174, 0xbfb8aa3b, v69
	v_exp_f32_e32 v171, v171
	v_exp_f32_e32 v172, v172
	v_exp_f32_e32 v173, v173
	v_exp_f32_e32 v174, v174
	s_nop 0
	v_add_f32_e32 v171, 1.0, v171
	v_add_f32_e32 v172, 1.0, v172
	v_add_f32_e32 v173, 1.0, v173
	v_add_f32_e32 v174, 1.0, v174
	v_rcp_f32_e32 v171, v171
	v_rcp_f32_e32 v172, v172
	v_rcp_f32_e32 v173, v173
	v_rcp_f32_e32 v174, v174
	s_nop 0
	v_mul_f32_e32 v171, v66, v171
	v_mul_f32_e32 v172, v67, v172
	v_mul_f32_e32 v173, v68, v173
	v_mul_f32_e32 v174, v69, v174
	v_mul_f32_e32 v171, v82, v171
	v_mul_f32_e32 v172, v83, v172
	v_mul_f32_e32 v173, v84, v173
	v_mul_f32_e32 v174, v85, v174
	v_cvt_pk_bf16_f32 v179, v171, v171
	v_cvt_pk_bf16_f32 v180, v172, v172
	v_cvt_pk_bf16_f32 v181, v173, v173
	v_cvt_pk_bf16_f32 v182, v174, v174
	global_store_short v162, v179, s[66:67]
	global_store_short v163, v180, s[66:67]
	global_store_short v164, v181, s[66:67]
	global_store_short v165, v182, s[66:67]
	s_add_u32 s66, s66, 0xb000
	s_addc_u32 s67, s67, 0
	v_mul_f32_e32 v171, 0xbfb8aa3b, v70
	v_mul_f32_e32 v172, 0xbfb8aa3b, v71
	v_mul_f32_e32 v173, 0xbfb8aa3b, v72
	v_mul_f32_e32 v174, 0xbfb8aa3b, v73
	v_exp_f32_e32 v171, v171
	v_exp_f32_e32 v172, v172
	v_exp_f32_e32 v173, v173
	v_exp_f32_e32 v174, v174
	s_nop 0
	v_add_f32_e32 v171, 1.0, v171
	v_add_f32_e32 v172, 1.0, v172
	v_add_f32_e32 v173, 1.0, v173
	v_add_f32_e32 v174, 1.0, v174
	v_rcp_f32_e32 v171, v171
	v_rcp_f32_e32 v172, v172
	v_rcp_f32_e32 v173, v173
	v_rcp_f32_e32 v174, v174
	s_nop 0
	v_mul_f32_e32 v171, v70, v171
	v_mul_f32_e32 v172, v71, v172
	v_mul_f32_e32 v173, v72, v173
	v_mul_f32_e32 v174, v73, v174
	v_mul_f32_e32 v171, v86, v171
	v_mul_f32_e32 v172, v87, v172
	v_mul_f32_e32 v173, v88, v173
	v_mul_f32_e32 v174, v89, v174
	v_cvt_pk_bf16_f32 v179, v171, v171
	v_cvt_pk_bf16_f32 v180, v172, v172
	v_cvt_pk_bf16_f32 v181, v173, v173
	v_cvt_pk_bf16_f32 v182, v174, v174
	global_store_short v162, v179, s[66:67]
	global_store_short v163, v180, s[66:67]
	global_store_short v164, v181, s[66:67]
	global_store_short v165, v182, s[66:67]
	s_add_u32 s66, s66, 0xb000
	s_addc_u32 s67, s67, 0
	v_mul_f32_e32 v171, 0xbfb8aa3b, v74
	v_mul_f32_e32 v172, 0xbfb8aa3b, v75
	v_mul_f32_e32 v173, 0xbfb8aa3b, v76
	v_mul_f32_e32 v174, 0xbfb8aa3b, v77
	v_exp_f32_e32 v171, v171
	v_exp_f32_e32 v172, v172
	v_exp_f32_e32 v173, v173
	v_exp_f32_e32 v174, v174
	s_nop 0
	v_add_f32_e32 v171, 1.0, v171
	v_add_f32_e32 v172, 1.0, v172
	v_add_f32_e32 v173, 1.0, v173
	v_add_f32_e32 v174, 1.0, v174
	v_rcp_f32_e32 v171, v171
	v_rcp_f32_e32 v172, v172
	v_rcp_f32_e32 v173, v173
	v_rcp_f32_e32 v174, v174
	s_nop 0
	v_mul_f32_e32 v171, v74, v171
	v_mul_f32_e32 v172, v75, v172
	v_mul_f32_e32 v173, v76, v173
	v_mul_f32_e32 v174, v77, v174
	v_mul_f32_e32 v171, v90, v171
	v_mul_f32_e32 v172, v91, v172
	v_mul_f32_e32 v173, v92, v173
	v_mul_f32_e32 v174, v93, v174
	v_cvt_pk_bf16_f32 v179, v171, v171
	v_cvt_pk_bf16_f32 v180, v172, v172
	v_cvt_pk_bf16_f32 v181, v173, v173
	v_cvt_pk_bf16_f32 v182, v174, v174
	global_store_short v162, v179, s[66:67]
	global_store_short v163, v180, s[66:67]
	global_store_short v164, v181, s[66:67]
	global_store_short v165, v182, s[66:67]
	s_add_u32 s66, s66, 0xb000
	s_addc_u32 s67, s67, 0
	v_mul_f32_e32 v171, 0xbfb8aa3b, v78
	v_mul_f32_e32 v172, 0xbfb8aa3b, v79
	v_mul_f32_e32 v173, 0xbfb8aa3b, v80
	v_mul_f32_e32 v174, 0xbfb8aa3b, v81
	v_exp_f32_e32 v171, v171
	v_exp_f32_e32 v172, v172
	v_exp_f32_e32 v173, v173
	v_exp_f32_e32 v174, v174
	s_nop 0
	v_add_f32_e32 v171, 1.0, v171
	v_add_f32_e32 v172, 1.0, v172
	v_add_f32_e32 v173, 1.0, v173
	v_add_f32_e32 v174, 1.0, v174
	v_rcp_f32_e32 v171, v171
	v_rcp_f32_e32 v172, v172
	v_rcp_f32_e32 v173, v173
	v_rcp_f32_e32 v174, v174
	s_nop 0
	v_mul_f32_e32 v171, v78, v171
	v_mul_f32_e32 v172, v79, v172
	v_mul_f32_e32 v173, v80, v173
	v_mul_f32_e32 v174, v81, v174
	v_mul_f32_e32 v171, v94, v171
	v_mul_f32_e32 v172, v95, v172
	v_mul_f32_e32 v173, v96, v173
	v_mul_f32_e32 v174, v97, v174
	v_cvt_pk_bf16_f32 v179, v171, v171
	v_cvt_pk_bf16_f32 v180, v172, v172
	v_cvt_pk_bf16_f32 v181, v173, v173
	v_cvt_pk_bf16_f32 v182, v174, v174
	global_store_short v162, v179, s[66:67]
	global_store_short v163, v180, s[66:67]
	global_store_short v164, v181, s[66:67]
	global_store_short v165, v182, s[66:67]
	s_add_u32 s66, s66, 0xb000
	s_addc_u32 s67, s67, 0
	v_mul_f32_e32 v171, 0xbfb8aa3b, v98
	v_mul_f32_e32 v172, 0xbfb8aa3b, v99
	v_mul_f32_e32 v173, 0xbfb8aa3b, v100
	v_mul_f32_e32 v174, 0xbfb8aa3b, v101
	v_exp_f32_e32 v171, v171
	v_exp_f32_e32 v172, v172
	v_exp_f32_e32 v173, v173
	v_exp_f32_e32 v174, v174
	s_nop 0
	v_add_f32_e32 v171, 1.0, v171
	v_add_f32_e32 v172, 1.0, v172
	v_add_f32_e32 v173, 1.0, v173
	v_add_f32_e32 v174, 1.0, v174
	v_rcp_f32_e32 v171, v171
	v_rcp_f32_e32 v172, v172
	v_rcp_f32_e32 v173, v173
	v_rcp_f32_e32 v174, v174
	s_nop 0
	v_mul_f32_e32 v171, v98, v171
	v_mul_f32_e32 v172, v99, v172
	v_mul_f32_e32 v173, v100, v173
	v_mul_f32_e32 v174, v101, v174
	v_mul_f32_e32 v171, v114, v171
	v_mul_f32_e32 v172, v115, v172
	v_mul_f32_e32 v173, v116, v173
	v_mul_f32_e32 v174, v117, v174
	v_cvt_pk_bf16_f32 v179, v171, v171
	v_cvt_pk_bf16_f32 v180, v172, v172
	v_cvt_pk_bf16_f32 v181, v173, v173
	v_cvt_pk_bf16_f32 v182, v174, v174
	global_store_short v162, v179, s[66:67]
	global_store_short v163, v180, s[66:67]
	global_store_short v164, v181, s[66:67]
	global_store_short v165, v182, s[66:67]
	s_add_u32 s66, s66, 0xb000
	s_addc_u32 s67, s67, 0
	v_mul_f32_e32 v171, 0xbfb8aa3b, v102
	v_mul_f32_e32 v172, 0xbfb8aa3b, v103
	v_mul_f32_e32 v173, 0xbfb8aa3b, v104
	v_mul_f32_e32 v174, 0xbfb8aa3b, v105
	v_exp_f32_e32 v171, v171
	v_exp_f32_e32 v172, v172
	v_exp_f32_e32 v173, v173
	v_exp_f32_e32 v174, v174
	s_nop 0
	v_add_f32_e32 v171, 1.0, v171
	v_add_f32_e32 v172, 1.0, v172
	v_add_f32_e32 v173, 1.0, v173
	v_add_f32_e32 v174, 1.0, v174
	v_rcp_f32_e32 v171, v171
	v_rcp_f32_e32 v172, v172
	v_rcp_f32_e32 v173, v173
	v_rcp_f32_e32 v174, v174
	s_nop 0
	v_mul_f32_e32 v171, v102, v171
	v_mul_f32_e32 v172, v103, v172
	v_mul_f32_e32 v173, v104, v173
	v_mul_f32_e32 v174, v105, v174
	v_mul_f32_e32 v171, v118, v171
	v_mul_f32_e32 v172, v119, v172
	v_mul_f32_e32 v173, v120, v173
	v_mul_f32_e32 v174, v121, v174
	v_cvt_pk_bf16_f32 v179, v171, v171
	v_cvt_pk_bf16_f32 v180, v172, v172
	v_cvt_pk_bf16_f32 v181, v173, v173
	v_cvt_pk_bf16_f32 v182, v174, v174
	global_store_short v162, v179, s[66:67]
	global_store_short v163, v180, s[66:67]
	global_store_short v164, v181, s[66:67]
	global_store_short v165, v182, s[66:67]
	s_add_u32 s66, s66, 0xb000
	s_addc_u32 s67, s67, 0
	v_mul_f32_e32 v171, 0xbfb8aa3b, v106
	v_mul_f32_e32 v172, 0xbfb8aa3b, v107
	v_mul_f32_e32 v173, 0xbfb8aa3b, v108
	v_mul_f32_e32 v174, 0xbfb8aa3b, v109
	v_exp_f32_e32 v171, v171
	v_exp_f32_e32 v172, v172
	v_exp_f32_e32 v173, v173
	v_exp_f32_e32 v174, v174
	s_nop 0
	v_add_f32_e32 v171, 1.0, v171
	v_add_f32_e32 v172, 1.0, v172
	v_add_f32_e32 v173, 1.0, v173
	v_add_f32_e32 v174, 1.0, v174
	v_rcp_f32_e32 v171, v171
	v_rcp_f32_e32 v172, v172
	v_rcp_f32_e32 v173, v173
	v_rcp_f32_e32 v174, v174
	s_nop 0
	v_mul_f32_e32 v171, v106, v171
	v_mul_f32_e32 v172, v107, v172
	v_mul_f32_e32 v173, v108, v173
	v_mul_f32_e32 v174, v109, v174
	v_mul_f32_e32 v171, v122, v171
	v_mul_f32_e32 v172, v123, v172
	v_mul_f32_e32 v173, v124, v173
	v_mul_f32_e32 v174, v125, v174
	v_cvt_pk_bf16_f32 v179, v171, v171
	v_cvt_pk_bf16_f32 v180, v172, v172
	v_cvt_pk_bf16_f32 v181, v173, v173
	v_cvt_pk_bf16_f32 v182, v174, v174
	global_store_short v162, v179, s[66:67]
	global_store_short v163, v180, s[66:67]
	global_store_short v164, v181, s[66:67]
	global_store_short v165, v182, s[66:67]
	s_add_u32 s66, s66, 0xb000
	s_addc_u32 s67, s67, 0
	v_mul_f32_e32 v171, 0xbfb8aa3b, v110
	v_mul_f32_e32 v172, 0xbfb8aa3b, v111
	v_mul_f32_e32 v173, 0xbfb8aa3b, v112
	v_mul_f32_e32 v174, 0xbfb8aa3b, v113
	v_exp_f32_e32 v171, v171
	v_exp_f32_e32 v172, v172
	v_exp_f32_e32 v173, v173
	v_exp_f32_e32 v174, v174
	s_nop 0
	v_add_f32_e32 v171, 1.0, v171
	v_add_f32_e32 v172, 1.0, v172
	v_add_f32_e32 v173, 1.0, v173
	v_add_f32_e32 v174, 1.0, v174
	v_rcp_f32_e32 v171, v171
	v_rcp_f32_e32 v172, v172
	v_rcp_f32_e32 v173, v173
	v_rcp_f32_e32 v174, v174
	s_nop 0
	v_mul_f32_e32 v171, v110, v171
	v_mul_f32_e32 v172, v111, v172
	v_mul_f32_e32 v173, v112, v173
	v_mul_f32_e32 v174, v113, v174
	v_mul_f32_e32 v171, v126, v171
	v_mul_f32_e32 v172, v127, v172
	v_mul_f32_e32 v173, v128, v173
	v_mul_f32_e32 v174, v129, v174
	v_cvt_pk_bf16_f32 v179, v171, v171
	v_cvt_pk_bf16_f32 v180, v172, v172
	v_cvt_pk_bf16_f32 v181, v173, v173
	v_cvt_pk_bf16_f32 v182, v174, v174
	global_store_short v162, v179, s[66:67]
	global_store_short v163, v180, s[66:67]
	global_store_short v164, v181, s[66:67]
	global_store_short v165, v182, s[66:67]
	v_readlane_b32 s62, v246, 14
	s_nop 0
	s_add_i32 s2, s2, s62
	s_branch .Lhw_ffnup_dloop

.Lhw_ffnup_sloop:
	s_sub_i32 s62, 0x108, s64
	s_lshl_b32 s62, s62, 1
	s_cmp_ge_u32 s2, s62
	s_cbranch_scc1 .Lhw_ffnup_exit
	s_lshr_b32 s63, s2, 1
	s_add_i32 s63, s63, s64
	s_mul_i32 s6, s63, 745
	s_lshr_b32 s6, s6, 16
	s_mul_i32 s14, s6, 88
	s_sub_i32 s14, s63, s14
	v_readlane_b32 s13, v246, 16
	s_lshl_b32 s6, s6, 2
	s_and_b32 s12, s14, 3
	s_add_i32 s6, s6, s12
	s_add_i32 s6, s6, s13
	s_lshl_b32 s6, s6, 7
	s_lshr_b32 s14, s14, 2
	s_lshl_b32 s14, s14, 8
	s_and_b32 s12, s2, 1
	s_lshl_b32 s12, s12, 7
	s_add_i32 s14, s14, s12
	s_lshl_b32 vcc_lo, s6, 11
	s_add_u32 s66, s10, vcc_lo
	s_addc_u32 s67, s11, 0
	s_lshl_b32 vcc_lo, s14, 11
	s_add_u32 s12, s0, vcc_lo
	s_addc_u32 s13, s1, 0
	s_barrier
	s_add_u32 m0, s65, 0x0
	s_nop 0
	global_load_lds_dwordx4 v160, s[66:67]
	s_add_u32 m0, s65, 0x1000
	s_nop 0
	global_load_lds_dwordx4 v161, s[66:67]
	s_add_u32 m0, s65, 0x2000
	s_nop 0
	global_load_lds_dwordx4 v160, s[12:13]
	s_add_u32 m0, s65, 0x3000
	s_nop 0
	global_load_lds_dwordx4 v161, s[12:13]
	s_add_u32 s66, s66, 64
	s_addc_u32 s67, s67, 0
	s_add_u32 s12, s12, 64
	s_addc_u32 s13, s13, 0
	s_add_u32 m0, s65, 0x6000
	s_nop 0
	global_load_lds_dwordx4 v160, s[66:67]
	s_add_u32 m0, s65, 0x7000
	s_nop 0
	global_load_lds_dwordx4 v161, s[66:67]
	s_add_u32 m0, s65, 0x8000
	s_nop 0
	global_load_lds_dwordx4 v160, s[12:13]
	s_add_u32 m0, s65, 0x9000
	s_nop 0
	global_load_lds_dwordx4 v161, s[12:13]
	s_add_u32 s66, s66, 64
	s_addc_u32 s67, s67, 0
	s_add_u32 s12, s12, 64
	s_addc_u32 s13, s13, 0
	v_mov_b32_e32 v2, 0
	v_mov_b32_e32 v3, 0
	v_mov_b32_e32 v4, 0
	v_mov_b32_e32 v5, 0
	v_mov_b32_e32 v6, 0
	v_mov_b32_e32 v7, 0
	v_mov_b32_e32 v8, 0
	v_mov_b32_e32 v9, 0
	v_mov_b32_e32 v10, 0
	v_mov_b32_e32 v11, 0
	v_mov_b32_e32 v12, 0
	v_mov_b32_e32 v13, 0
	v_mov_b32_e32 v14, 0
	v_mov_b32_e32 v15, 0
	v_mov_b32_e32 v16, 0
	v_mov_b32_e32 v17, 0
	v_mov_b32_e32 v18, 0
	v_mov_b32_e32 v19, 0
	v_mov_b32_e32 v20, 0
	v_mov_b32_e32 v21, 0
	v_mov_b32_e32 v22, 0
	v_mov_b32_e32 v23, 0
	v_mov_b32_e32 v24, 0
	v_mov_b32_e32 v25, 0
	v_mov_b32_e32 v26, 0
	v_mov_b32_e32 v27, 0
	v_mov_b32_e32 v28, 0
	v_mov_b32_e32 v29, 0
	v_mov_b32_e32 v30, 0
	v_mov_b32_e32 v31, 0
	v_mov_b32_e32 v32, 0
	v_mov_b32_e32 v33, 0
	v_mov_b32_e32 v34, 0
	v_mov_b32_e32 v35, 0
	v_mov_b32_e32 v36, 0
	v_mov_b32_e32 v37, 0
	v_mov_b32_e32 v38, 0
	v_mov_b32_e32 v39, 0
	v_mov_b32_e32 v40, 0
	v_mov_b32_e32 v41, 0
	v_mov_b32_e32 v42, 0
	v_mov_b32_e32 v43, 0
	v_mov_b32_e32 v44, 0
	v_mov_b32_e32 v45, 0
	v_mov_b32_e32 v46, 0
	v_mov_b32_e32 v47, 0
	v_mov_b32_e32 v48, 0
	v_mov_b32_e32 v49, 0
	v_mov_b32_e32 v50, 0
	v_mov_b32_e32 v51, 0
	v_mov_b32_e32 v52, 0
	v_mov_b32_e32 v53, 0
	v_mov_b32_e32 v54, 0
	v_mov_b32_e32 v55, 0
	v_mov_b32_e32 v56, 0
	v_mov_b32_e32 v57, 0
	v_mov_b32_e32 v58, 0
	v_mov_b32_e32 v59, 0
	v_mov_b32_e32 v60, 0
	v_mov_b32_e32 v61, 0
	v_mov_b32_e32 v62, 0
	v_mov_b32_e32 v63, 0
	v_mov_b32_e32 v64, 0
	v_mov_b32_e32 v65, 0
	s_waitcnt vmcnt(4)
	s_barrier
	ds_read_b128 v[130:133], v154 offset:16
	ds_read_b128 v[138:141], v156 offset:8208
	ds_read_b128 v[142:145], v156 offset:10256
	ds_read_b128 v[134:137], v154 offset:2064
	s_mov_b32 s59, 10
.Lhw_ffnup_s_loop:
	s_waitcnt vmcnt(0)
	s_barrier
	s_waitcnt lgkmcnt(0)
	v_mfma_f32_32x32x16_bf16 v[2:17], v[130:133], v[138:141], v[2:17]
	ds_read_b128 v[212:215], v155 offset:16
	s_add_u32 m0, s65, 0xc000
	v_mfma_f32_32x32x16_bf16 v[18:33], v[130:133], v[142:145], v[18:33]
	ds_read_b128 v[220:223], v157 offset:8208
	global_load_lds_dwordx4 v160, s[66:67]
	v_mfma_f32_32x32x16_bf16 v[34:49], v[134:137], v[138:141], v[34:49]
	ds_read_b128 v[224:227], v157 offset:10256
	s_add_u32 m0, s65, 0xd000
	v_mfma_f32_32x32x16_bf16 v[50:65], v[134:137], v[142:145], v[50:65]
	ds_read_b128 v[216:219], v155 offset:2064
	global_load_lds_dwordx4 v161, s[66:67]
	s_waitcnt lgkmcnt(2)
	v_mfma_f32_32x32x16_bf16 v[2:17], v[212:215], v[220:223], v[2:17]
	s_add_u32 m0, s65, 0xe000
	ds_read_b128 v[130:133], v154 offset:24592
	s_waitcnt lgkmcnt(2)
	v_mfma_f32_32x32x16_bf16 v[18:33], v[212:215], v[224:227], v[18:33]
	global_load_lds_dwordx4 v160, s[12:13]
	ds_read_b128 v[138:141], v156 offset:32784
	s_waitcnt lgkmcnt(2)
	v_mfma_f32_32x32x16_bf16 v[34:49], v[216:219], v[220:223], v[34:49]
	s_add_u32 m0, s65, 0xf000
	ds_read_b128 v[142:145], v156 offset:34832
	s_waitcnt lgkmcnt(3)
	v_mfma_f32_32x32x16_bf16 v[50:65], v[216:219], v[224:227], v[50:65]
	global_load_lds_dwordx4 v161, s[12:13]
	s_add_u32 s66, s66, 64
	s_addc_u32 s67, s67, 0
	s_add_u32 s12, s12, 64
	s_addc_u32 s13, s13, 0
	ds_read_b128 v[134:137], v154 offset:26640
	s_waitcnt vmcnt(0)
	s_barrier
	s_waitcnt lgkmcnt(0)
	v_mfma_f32_32x32x16_bf16 v[2:17], v[130:133], v[138:141], v[2:17]
	ds_read_b128 v[212:215], v155 offset:24592
	s_add_u32 m0, s65, 0x0
	v_mfma_f32_32x32x16_bf16 v[18:33], v[130:133], v[142:145], v[18:33]
	ds_read_b128 v[220:223], v157 offset:32784
	global_load_lds_dwordx4 v160, s[66:67]
	v_mfma_f32_32x32x16_bf16 v[34:49], v[134:137], v[138:141], v[34:49]
	ds_read_b128 v[224:227], v157 offset:34832
	s_add_u32 m0, s65, 0x1000
	v_mfma_f32_32x32x16_bf16 v[50:65], v[134:137], v[142:145], v[50:65]
	ds_read_b128 v[216:219], v155 offset:26640
	global_load_lds_dwordx4 v161, s[66:67]
	s_waitcnt lgkmcnt(2)
	v_mfma_f32_32x32x16_bf16 v[2:17], v[212:215], v[220:223], v[2:17]
	s_add_u32 m0, s65, 0x2000
	ds_read_b128 v[130:133], v154 offset:49168
	s_waitcnt lgkmcnt(2)
	v_mfma_f32_32x32x16_bf16 v[18:33], v[212:215], v[224:227], v[18:33]
	global_load_lds_dwordx4 v160, s[12:13]
	ds_read_b128 v[138:141], v156 offset:57360
	s_waitcnt lgkmcnt(2)
	v_mfma_f32_32x32x16_bf16 v[34:49], v[216:219], v[220:223], v[34:49]
	s_add_u32 m0, s65, 0x3000
	ds_read_b128 v[142:145], v156 offset:59408
	s_waitcnt lgkmcnt(3)
	v_mfma_f32_32x32x16_bf16 v[50:65], v[216:219], v[224:227], v[50:65]
	global_load_lds_dwordx4 v161, s[12:13]
	s_add_u32 s66, s66, 64
	s_addc_u32 s67, s67, 0
	s_add_u32 s12, s12, 64
	s_addc_u32 s13, s13, 0
	ds_read_b128 v[134:137], v154 offset:51216
	s_waitcnt vmcnt(0)
	s_barrier
	s_waitcnt lgkmcnt(0)
	v_mfma_f32_32x32x16_bf16 v[2:17], v[130:133], v[138:141], v[2:17]
	ds_read_b128 v[212:215], v155 offset:49168
	s_add_u32 m0, s65, 0x6000
	v_mfma_f32_32x32x16_bf16 v[18:33], v[130:133], v[142:145], v[18:33]
	ds_read_b128 v[220:223], v157 offset:57360
	global_load_lds_dwordx4 v160, s[66:67]
	v_mfma_f32_32x32x16_bf16 v[34:49], v[134:137], v[138:141], v[34:49]
	ds_read_b128 v[224:227], v157 offset:59408
	s_add_u32 m0, s65, 0x7000
	v_mfma_f32_32x32x16_bf16 v[50:65], v[134:137], v[142:145], v[50:65]
	ds_read_b128 v[216:219], v155 offset:51216
	global_load_lds_dwordx4 v161, s[66:67]
	s_waitcnt lgkmcnt(2)
	v_mfma_f32_32x32x16_bf16 v[2:17], v[212:215], v[220:223], v[2:17]
	s_add_u32 m0, s65, 0x8000
	ds_read_b128 v[130:133], v154 offset:16
	s_waitcnt lgkmcnt(2)
	v_mfma_f32_32x32x16_bf16 v[18:33], v[212:215], v[224:227], v[18:33]
	global_load_lds_dwordx4 v160, s[12:13]
	ds_read_b128 v[138:141], v156 offset:8208
	s_waitcnt lgkmcnt(2)
	v_mfma_f32_32x32x16_bf16 v[34:49], v[216:219], v[220:223], v[34:49]
	s_add_u32 m0, s65, 0x9000
	ds_read_b128 v[142:145], v156 offset:10256
	s_waitcnt lgkmcnt(3)
	v_mfma_f32_32x32x16_bf16 v[50:65], v[216:219], v[224:227], v[50:65]
	global_load_lds_dwordx4 v161, s[12:13]
	s_add_u32 s66, s66, 64
	s_addc_u32 s67, s67, 0
	s_add_u32 s12, s12, 64
	s_addc_u32 s13, s13, 0
	ds_read_b128 v[134:137], v154 offset:2064
	s_sub_u32 s59, s59, 1
	s_cmp_lg_u32 s59, 0
	s_cbranch_scc1 .Lhw_ffnup_s_loop
	s_waitcnt vmcnt(0)
	s_barrier
	s_waitcnt lgkmcnt(0)
	v_mfma_f32_32x32x16_bf16 v[2:17], v[130:133], v[138:141], v[2:17]
	ds_read_b128 v[212:215], v155 offset:16
	v_mfma_f32_32x32x16_bf16 v[18:33], v[130:133], v[142:145], v[18:33]
	ds_read_b128 v[220:223], v157 offset:8208
	v_mfma_f32_32x32x16_bf16 v[34:49], v[134:137], v[138:141], v[34:49]
	ds_read_b128 v[224:227], v157 offset:10256
	v_mfma_f32_32x32x16_bf16 v[50:65], v[134:137], v[142:145], v[50:65]
	ds_read_b128 v[216:219], v155 offset:2064
	s_waitcnt lgkmcnt(2)
	v_mfma_f32_32x32x16_bf16 v[2:17], v[212:215], v[220:223], v[2:17]
	ds_read_b128 v[130:133], v154 offset:24592
	s_waitcnt lgkmcnt(2)
	v_mfma_f32_32x32x16_bf16 v[18:33], v[212:215], v[224:227], v[18:33]
	ds_read_b128 v[138:141], v156 offset:32784
	s_waitcnt lgkmcnt(2)
	v_mfma_f32_32x32x16_bf16 v[34:49], v[216:219], v[220:223], v[34:49]
	ds_read_b128 v[142:145], v156 offset:34832
	s_waitcnt lgkmcnt(3)
	v_mfma_f32_32x32x16_bf16 v[50:65], v[216:219], v[224:227], v[50:65]
	ds_read_b128 v[134:137], v154 offset:26640
	s_waitcnt lgkmcnt(0)
	v_mfma_f32_32x32x16_bf16 v[2:17], v[130:133], v[138:141], v[2:17]
	ds_read_b128 v[212:215], v155 offset:24592
	v_mfma_f32_32x32x16_bf16 v[18:33], v[130:133], v[142:145], v[18:33]
	ds_read_b128 v[220:223], v157 offset:32784
	v_mfma_f32_32x32x16_bf16 v[34:49], v[134:137], v[138:141], v[34:49]
	ds_read_b128 v[224:227], v157 offset:34832
	v_mfma_f32_32x32x16_bf16 v[50:65], v[134:137], v[142:145], v[50:65]
	ds_read_b128 v[216:219], v155 offset:26640
	s_waitcnt lgkmcnt(2)
	v_mfma_f32_32x32x16_bf16 v[2:17], v[212:215], v[220:223], v[2:17]
	s_waitcnt lgkmcnt(1)
	v_mfma_f32_32x32x16_bf16 v[18:33], v[212:215], v[224:227], v[18:33]
	s_waitcnt lgkmcnt(0)
	v_mfma_f32_32x32x16_bf16 v[34:49], v[216:219], v[220:223], v[34:49]
	s_waitcnt lgkmcnt(0)
	v_mfma_f32_32x32x16_bf16 v[50:65], v[216:219], v[224:227], v[50:65]
	s_nop 7
	s_nop 7
	s_mul_i32 vcc_lo, s6, 0x1600
	s_add_u32 s66, s8, vcc_lo
	s_addc_u32 s67, s9, 0
	s_add_u32 s66, s66, s14
	s_addc_u32 s67, s67, 0
	v_mul_f32_e32 v171, 0xbfb8aa3b, v2
	v_mul_f32_e32 v172, 0xbfb8aa3b, v3
	v_mul_f32_e32 v173, 0xbfb8aa3b, v4
	v_mul_f32_e32 v174, 0xbfb8aa3b, v5
	v_exp_f32_e32 v171, v171
	v_exp_f32_e32 v172, v172
	v_exp_f32_e32 v173, v173
	v_exp_f32_e32 v174, v174
	s_nop 0
	v_add_f32_e32 v171, 1.0, v171
	v_add_f32_e32 v172, 1.0, v172
	v_add_f32_e32 v173, 1.0, v173
	v_add_f32_e32 v174, 1.0, v174
	v_rcp_f32_e32 v171, v171
	v_rcp_f32_e32 v172, v172
	v_rcp_f32_e32 v173, v173
	v_rcp_f32_e32 v174, v174
	s_nop 0
	v_mul_f32_e32 v171, v2, v171
	v_mul_f32_e32 v172, v3, v172
	v_mul_f32_e32 v173, v4, v173
	v_mul_f32_e32 v174, v5, v174
	v_mul_f32_e32 v171, v18, v171
	v_mul_f32_e32 v172, v19, v172
	v_mul_f32_e32 v173, v20, v173
	v_mul_f32_e32 v174, v21, v174
	v_cvt_pk_bf16_f32 v179, v171, v171
	v_cvt_pk_bf16_f32 v180, v172, v172
	v_cvt_pk_bf16_f32 v181, v173, v173
	v_cvt_pk_bf16_f32 v182, v174, v174
	global_store_short v162, v179, s[66:67]
	global_store_short v163, v180, s[66:67]
	global_store_short v164, v181, s[66:67]
	global_store_short v165, v182, s[66:67]
	s_add_u32 s66, s66, 0xb000
	s_addc_u32 s67, s67, 0
	v_mul_f32_e32 v171, 0xbfb8aa3b, v6
	v_mul_f32_e32 v172, 0xbfb8aa3b, v7
	v_mul_f32_e32 v173, 0xbfb8aa3b, v8
	v_mul_f32_e32 v174, 0xbfb8aa3b, v9
	v_exp_f32_e32 v171, v171
	v_exp_f32_e32 v172, v172
	v_exp_f32_e32 v173, v173
	v_exp_f32_e32 v174, v174
	s_nop 0
	v_add_f32_e32 v171, 1.0, v171
	v_add_f32_e32 v172, 1.0, v172
	v_add_f32_e32 v173, 1.0, v173
	v_add_f32_e32 v174, 1.0, v174
	v_rcp_f32_e32 v171, v171
	v_rcp_f32_e32 v172, v172
	v_rcp_f32_e32 v173, v173
	v_rcp_f32_e32 v174, v174
	s_nop 0
	v_mul_f32_e32 v171, v6, v171
	v_mul_f32_e32 v172, v7, v172
	v_mul_f32_e32 v173, v8, v173
	v_mul_f32_e32 v174, v9, v174
	v_mul_f32_e32 v171, v22, v171
	v_mul_f32_e32 v172, v23, v172
	v_mul_f32_e32 v173, v24, v173
	v_mul_f32_e32 v174, v25, v174
	v_cvt_pk_bf16_f32 v179, v171, v171
	v_cvt_pk_bf16_f32 v180, v172, v172
	v_cvt_pk_bf16_f32 v181, v173, v173
	v_cvt_pk_bf16_f32 v182, v174, v174
	global_store_short v162, v179, s[66:67]
	global_store_short v163, v180, s[66:67]
	global_store_short v164, v181, s[66:67]
	global_store_short v165, v182, s[66:67]
	s_add_u32 s66, s66, 0xb000
	s_addc_u32 s67, s67, 0
	v_mul_f32_e32 v171, 0xbfb8aa3b, v10
	v_mul_f32_e32 v172, 0xbfb8aa3b, v11
	v_mul_f32_e32 v173, 0xbfb8aa3b, v12
	v_mul_f32_e32 v174, 0xbfb8aa3b, v13
	v_exp_f32_e32 v171, v171
	v_exp_f32_e32 v172, v172
	v_exp_f32_e32 v173, v173
	v_exp_f32_e32 v174, v174
	s_nop 0
	v_add_f32_e32 v171, 1.0, v171
	v_add_f32_e32 v172, 1.0, v172
	v_add_f32_e32 v173, 1.0, v173
	v_add_f32_e32 v174, 1.0, v174
	v_rcp_f32_e32 v171, v171
	v_rcp_f32_e32 v172, v172
	v_rcp_f32_e32 v173, v173
	v_rcp_f32_e32 v174, v174
	s_nop 0
	v_mul_f32_e32 v171, v10, v171
	v_mul_f32_e32 v172, v11, v172
	v_mul_f32_e32 v173, v12, v173
	v_mul_f32_e32 v174, v13, v174
	v_mul_f32_e32 v171, v26, v171
	v_mul_f32_e32 v172, v27, v172
	v_mul_f32_e32 v173, v28, v173
	v_mul_f32_e32 v174, v29, v174
	v_cvt_pk_bf16_f32 v179, v171, v171
	v_cvt_pk_bf16_f32 v180, v172, v172
	v_cvt_pk_bf16_f32 v181, v173, v173
	v_cvt_pk_bf16_f32 v182, v174, v174
	global_store_short v162, v179, s[66:67]
	global_store_short v163, v180, s[66:67]
	global_store_short v164, v181, s[66:67]
	global_store_short v165, v182, s[66:67]
	s_add_u32 s66, s66, 0xb000
	s_addc_u32 s67, s67, 0
	v_mul_f32_e32 v171, 0xbfb8aa3b, v14
	v_mul_f32_e32 v172, 0xbfb8aa3b, v15
	v_mul_f32_e32 v173, 0xbfb8aa3b, v16
	v_mul_f32_e32 v174, 0xbfb8aa3b, v17
	v_exp_f32_e32 v171, v171
	v_exp_f32_e32 v172, v172
	v_exp_f32_e32 v173, v173
	v_exp_f32_e32 v174, v174
	s_nop 0
	v_add_f32_e32 v171, 1.0, v171
	v_add_f32_e32 v172, 1.0, v172
	v_add_f32_e32 v173, 1.0, v173
	v_add_f32_e32 v174, 1.0, v174
	v_rcp_f32_e32 v171, v171
	v_rcp_f32_e32 v172, v172
	v_rcp_f32_e32 v173, v173
	v_rcp_f32_e32 v174, v174
	s_nop 0
	v_mul_f32_e32 v171, v14, v171
	v_mul_f32_e32 v172, v15, v172
	v_mul_f32_e32 v173, v16, v173
	v_mul_f32_e32 v174, v17, v174
	v_mul_f32_e32 v171, v30, v171
	v_mul_f32_e32 v172, v31, v172
	v_mul_f32_e32 v173, v32, v173
	v_mul_f32_e32 v174, v33, v174
	v_cvt_pk_bf16_f32 v179, v171, v171
	v_cvt_pk_bf16_f32 v180, v172, v172
	v_cvt_pk_bf16_f32 v181, v173, v173
	v_cvt_pk_bf16_f32 v182, v174, v174
	global_store_short v162, v179, s[66:67]
	global_store_short v163, v180, s[66:67]
	global_store_short v164, v181, s[66:67]
	global_store_short v165, v182, s[66:67]
	s_add_u32 s66, s66, 0xb000
	s_addc_u32 s67, s67, 0
	v_mul_f32_e32 v171, 0xbfb8aa3b, v34
	v_mul_f32_e32 v172, 0xbfb8aa3b, v35
	v_mul_f32_e32 v173, 0xbfb8aa3b, v36
	v_mul_f32_e32 v174, 0xbfb8aa3b, v37
	v_exp_f32_e32 v171, v171
	v_exp_f32_e32 v172, v172
	v_exp_f32_e32 v173, v173
	v_exp_f32_e32 v174, v174
	s_nop 0
	v_add_f32_e32 v171, 1.0, v171
	v_add_f32_e32 v172, 1.0, v172
	v_add_f32_e32 v173, 1.0, v173
	v_add_f32_e32 v174, 1.0, v174
	v_rcp_f32_e32 v171, v171
	v_rcp_f32_e32 v172, v172
	v_rcp_f32_e32 v173, v173
	v_rcp_f32_e32 v174, v174
	s_nop 0
	v_mul_f32_e32 v171, v34, v171
	v_mul_f32_e32 v172, v35, v172
	v_mul_f32_e32 v173, v36, v173
	v_mul_f32_e32 v174, v37, v174
	v_mul_f32_e32 v171, v50, v171
	v_mul_f32_e32 v172, v51, v172
	v_mul_f32_e32 v173, v52, v173
	v_mul_f32_e32 v174, v53, v174
	v_cvt_pk_bf16_f32 v179, v171, v171
	v_cvt_pk_bf16_f32 v180, v172, v172
	v_cvt_pk_bf16_f32 v181, v173, v173
	v_cvt_pk_bf16_f32 v182, v174, v174
	global_store_short v162, v179, s[66:67]
	global_store_short v163, v180, s[66:67]
	global_store_short v164, v181, s[66:67]
	global_store_short v165, v182, s[66:67]
	s_add_u32 s66, s66, 0xb000
	s_addc_u32 s67, s67, 0
	v_mul_f32_e32 v171, 0xbfb8aa3b, v38
	v_mul_f32_e32 v172, 0xbfb8aa3b, v39
	v_mul_f32_e32 v173, 0xbfb8aa3b, v40
	v_mul_f32_e32 v174, 0xbfb8aa3b, v41
	v_exp_f32_e32 v171, v171
	v_exp_f32_e32 v172, v172
	v_exp_f32_e32 v173, v173
	v_exp_f32_e32 v174, v174
	s_nop 0
	v_add_f32_e32 v171, 1.0, v171
	v_add_f32_e32 v172, 1.0, v172
	v_add_f32_e32 v173, 1.0, v173
	v_add_f32_e32 v174, 1.0, v174
	v_rcp_f32_e32 v171, v171
	v_rcp_f32_e32 v172, v172
	v_rcp_f32_e32 v173, v173
	v_rcp_f32_e32 v174, v174
	s_nop 0
	v_mul_f32_e32 v171, v38, v171
	v_mul_f32_e32 v172, v39, v172
	v_mul_f32_e32 v173, v40, v173
	v_mul_f32_e32 v174, v41, v174
	v_mul_f32_e32 v171, v54, v171
	v_mul_f32_e32 v172, v55, v172
	v_mul_f32_e32 v173, v56, v173
	v_mul_f32_e32 v174, v57, v174
	v_cvt_pk_bf16_f32 v179, v171, v171
	v_cvt_pk_bf16_f32 v180, v172, v172
	v_cvt_pk_bf16_f32 v181, v173, v173
	v_cvt_pk_bf16_f32 v182, v174, v174
	global_store_short v162, v179, s[66:67]
	global_store_short v163, v180, s[66:67]
	global_store_short v164, v181, s[66:67]
	global_store_short v165, v182, s[66:67]
	s_add_u32 s66, s66, 0xb000
	s_addc_u32 s67, s67, 0
	v_mul_f32_e32 v171, 0xbfb8aa3b, v42
	v_mul_f32_e32 v172, 0xbfb8aa3b, v43
	v_mul_f32_e32 v173, 0xbfb8aa3b, v44
	v_mul_f32_e32 v174, 0xbfb8aa3b, v45
	v_exp_f32_e32 v171, v171
	v_exp_f32_e32 v172, v172
	v_exp_f32_e32 v173, v173
	v_exp_f32_e32 v174, v174
	s_nop 0
	v_add_f32_e32 v171, 1.0, v171
	v_add_f32_e32 v172, 1.0, v172
	v_add_f32_e32 v173, 1.0, v173
	v_add_f32_e32 v174, 1.0, v174
	v_rcp_f32_e32 v171, v171
	v_rcp_f32_e32 v172, v172
	v_rcp_f32_e32 v173, v173
	v_rcp_f32_e32 v174, v174
	s_nop 0
	v_mul_f32_e32 v171, v42, v171
	v_mul_f32_e32 v172, v43, v172
	v_mul_f32_e32 v173, v44, v173
	v_mul_f32_e32 v174, v45, v174
	v_mul_f32_e32 v171, v58, v171
	v_mul_f32_e32 v172, v59, v172
	v_mul_f32_e32 v173, v60, v173
	v_mul_f32_e32 v174, v61, v174
	v_cvt_pk_bf16_f32 v179, v171, v171
	v_cvt_pk_bf16_f32 v180, v172, v172
	v_cvt_pk_bf16_f32 v181, v173, v173
	v_cvt_pk_bf16_f32 v182, v174, v174
	global_store_short v162, v179, s[66:67]
	global_store_short v163, v180, s[66:67]
	global_store_short v164, v181, s[66:67]
	global_store_short v165, v182, s[66:67]
	s_add_u32 s66, s66, 0xb000
	s_addc_u32 s67, s67, 0
	v_mul_f32_e32 v171, 0xbfb8aa3b, v46
	v_mul_f32_e32 v172, 0xbfb8aa3b, v47
	v_mul_f32_e32 v173, 0xbfb8aa3b, v48
	v_mul_f32_e32 v174, 0xbfb8aa3b, v49
	v_exp_f32_e32 v171, v171
	v_exp_f32_e32 v172, v172
	v_exp_f32_e32 v173, v173
	v_exp_f32_e32 v174, v174
	s_nop 0
	v_add_f32_e32 v171, 1.0, v171
	v_add_f32_e32 v172, 1.0, v172
	v_add_f32_e32 v173, 1.0, v173
	v_add_f32_e32 v174, 1.0, v174
	v_rcp_f32_e32 v171, v171
	v_rcp_f32_e32 v172, v172
	v_rcp_f32_e32 v173, v173
	v_rcp_f32_e32 v174, v174
	s_nop 0
	v_mul_f32_e32 v171, v46, v171
	v_mul_f32_e32 v172, v47, v172
	v_mul_f32_e32 v173, v48, v173
	v_mul_f32_e32 v174, v49, v174
	v_mul_f32_e32 v171, v62, v171
	v_mul_f32_e32 v172, v63, v172
	v_mul_f32_e32 v173, v64, v173
	v_mul_f32_e32 v174, v65, v174
	v_cvt_pk_bf16_f32 v179, v171, v171
	v_cvt_pk_bf16_f32 v180, v172, v172
	v_cvt_pk_bf16_f32 v181, v173, v173
	v_cvt_pk_bf16_f32 v182, v174, v174
	global_store_short v162, v179, s[66:67]
	global_store_short v163, v180, s[66:67]
	global_store_short v164, v181, s[66:67]
	global_store_short v165, v182, s[66:67]
	v_readlane_b32 s62, v246, 14
	s_nop 0
	s_add_i32 s2, s2, s62
	s_branch .Lhw_ffnup_sloop
.Lhw_ffnup_exit:
	s_getpc_b64 s[98:99]
